# pair8h plus P0 weight items of the 64-row blocks renumbered: the four 64-deep K blocks that fill one 128-byte line of an fp4 row are converted by four neighbouring waves of one CU in the same step
# speedup vs baseline: 1.0028x; 1.0028x over previous
; __device__ __forceinline__ void p0_prologue(const Frame& F) {
;     ...
;     for (int it = gw; it < NITEMS; it += NGW) {
;         int r = it;
;         if (r < I_6) { const int kt = r / NB6, nb = r % NB6;
;             if (nb < 384) p0_transpose_pair_fp6(F.w_in, DM, NIN, 6144 + 32 * nb, F.WinT8, 32 * nb, scr, 2 * kt, plane);
;             else          p0_transpose_pair_fp6(F.w_in, DM, NIN, 24576 + 32 * (nb - 384), F.WinT8, 12288 + 32 * (nb - 384), scr, 2 * kt, plane);
;             continue; } r -= I_6;
;         if (r < I_IN) { const int kb = r / NBO, nb = r % NBO;
;             if (nb < 192) { const int n0 = 32 * nb;
;                 const int r0 = n0 < 2048 ? (n0 >> 7) * 256 + (n0 & 127) : (n0 < 4096 ? 4096 + (n0 - 2048) : ((n0 - 4096) >> 7) * 256 + 128 + ((n0 - 4096) & 127));
;                 p0_transpose_item_cols(F.w_in, DM, NIN, n0, F.WinT16, r0, scr, kb, plane); }
;             else if (nb < 384)  p0_transpose_item_fp4(F.w_in, DM, NIN, 18432 + 32 * (nb - 192), F.WinT4, 32 * (nb - 192), scr, kb, plane);
;             else                p0_transpose_item_fp4(F.w_in, DM, NIN, 30720 + 32 * (nb - 384), F.WinT4, 6144 + 32 * (nb - 384), scr, kb, plane);
.LBB0_26:
	s_andn2_b64 vcc, exec, s[58:59]
	s_cbranch_vccnz .LBB0_43
	s_add_i32 s0, s70, 0xffffb800
	s_lshr_b32 s66, s0, 11
	s_lshl_b32 s66, s66, 2
	s_and_b32 s98, s0, 3
	s_or_b32 s66, s66, s98
	s_bfe_u32 s0, s0, 0x90002
	s_lshl_b32 s99, s66, 9
	s_add_i32 s99, s99, s0
	s_addk_i32 s99, 0x4800
	s_lshl_b32 s100, s99, 6
	s_lshl_b32 s99, s99, 5
	s_cmpk_gt_u32 s0, 0xbf
	s_mov_b64 s[58:59], -1
	s_cbranch_scc0 .LBB0_33
	s_lshl_b32 s62, s0, 5
	s_lshl_b32 s67, s66, 6
	s_lshl_b32 s58, s0, 7
	s_add_u32 s58, s16, s58
	v_or_b32_e32 v0, s67, v64
	s_addc_u32 s59, s17, 0
	s_add_i32 s71, s62, 0xffffe800
	v_mul_lo_u32 v32, v0, s51
	v_or_b32_e32 v0, s67, v65
	v_mul_lo_u32 v18, v0, s51
	v_or_b32_e32 v0, s67, v67
	v_or_b32_e32 v1, s67, v69
	v_or_b32_e32 v2, s67, v70
	v_or_b32_e32 v3, s67, v71
	v_or_b32_e32 v4, s67, v72
	v_or_b32_e32 v5, s67, v73
	v_or_b32_e32 v6, s67, v36
	v_or_b32_e32 v7, s71, v64
	v_or_b32_e32 v9, s71, v65
	v_or_b32_e32 v11, s71, v67
	v_or_b32_e32 v13, s71, v69
	s_cmpk_gt_u32 s0, 0x17f
	v_mov_b32_e32 v19, v33
	s_mov_b64 s[62:63], -1
	v_mul_lo_u32 v22, v0, s51
	v_mul_lo_u32 v20, v1, s51
	v_mul_lo_u32 v16, v2, s51
	v_mul_lo_u32 v14, v3, s51
	v_mul_lo_u32 v12, v4, s51
	v_mul_lo_u32 v10, v5, s51
	v_lshrrev_b32_e32 v8, 1, v6
	v_lshlrev_b32_e32 v6, 11, v7
	v_lshlrev_b32_e32 v4, 11, v9
	v_lshlrev_b32_e32 v2, 11, v11
	v_lshlrev_b32_e32 v0, 11, v13
	s_cbranch_scc0 .LBB0_30
; #define LAS __attribute__((address_space(3)))
; #define LDS_WAIT() asm volatile("s_waitcnt lgkmcnt(0)" ::: "memory")
; __device__ __forceinline__ void p0_transpose_item_fp4(const float* W, int K, int N, int ncol0, unsigned char* WT4, int row0, LAS float* scr, int kb, int lane) {
;     const int k0 = 64 * kb;
; #pragma unroll 8
;     for (int i = 0; i < 8; ++i) { const int kk = 8 * i + (lane >> 3), n4 = (lane & 7) * 4;
;         const f32x4 v4 = *(const f32x4*)(W + (size_t)(k0 + kk) * N + ncol0 + n4); LAS float* d4 = scr + kk * 33 + n4; d4[0] = v4[0]; d4[1] = v4[1]; d4[2] = v4[2]; d4[3] = v4[3]; }
;     LDS_WAIT(); asm volatile("" ::: "memory");
;     const int c = lane & 7;
; #pragma unroll
;     for (int j = 0; j < 4; ++j) { const int n = (lane >> 3) + 8 * j; const LAS float* s = scr + (8 * c) * 33 + n;
;         const float v[8] = {s[0 * 33], s[1 * 33], s[2 * 33], s[3 * 33], s[4 * 33], s[5 * 33], s[6 * 33], s[7 * 33]};
;         *(unsigned*)(WT4 + (size_t)(row0 + n) * (K / 2) + (k0 + 8 * c) / 2) = q4x8(v, W4_SCALE); }
;     LDS_WAIT(); asm volatile("" ::: "memory");
; }
	v_lshlrev_b32_e32 v24, 2, v34
	v_mov_b32_e32 v25, v33
	v_lshl_add_u64 v[24:25], s[58:59], 0, v[24:25]
	v_lshl_add_u64 v[108:109], v[24:25], 0, s[4:5]
	v_mov_b32_e32 v23, v33
	v_mov_b32_e32 v21, v33
	v_mov_b32_e32 v17, v33
	v_mov_b32_e32 v15, v33
	v_lshl_add_u64 v[24:25], v[32:33], 2, v[108:109]
	v_lshl_add_u64 v[28:29], v[18:19], 2, v[108:109]
	v_lshl_add_u64 v[56:57], v[22:23], 2, v[108:109]
	v_lshl_add_u64 v[60:61], v[20:21], 2, v[108:109]
	v_lshl_add_u64 v[96:97], v[16:17], 2, v[108:109]
	v_lshl_add_u64 v[100:101], v[14:15], 2, v[108:109]
	global_load_dwordx4 v[24:27], v[24:25], off
	s_nop 0
	global_load_dwordx4 v[28:31], v[28:29], off
	s_nop 0
	global_load_dwordx4 v[56:59], v[56:57], off
	s_nop 0
	global_load_dwordx4 v[60:63], v[60:61], off
	s_nop 0
	global_load_dwordx4 v[96:99], v[96:97], off
	s_nop 0
	global_load_dwordx4 v[100:103], v[100:101], off
	v_mov_b32_e32 v13, v33
	v_lshl_add_u64 v[104:105], v[12:13], 2, v[108:109]
	global_load_dwordx4 v[104:107], v[104:105], off
	v_mov_b32_e32 v11, v33
	v_lshl_add_u64 v[108:109], v[10:11], 2, v[108:109]
	global_load_dwordx4 v[108:111], v[108:109], off
	v_mov_b32_e32 v9, v33
	v_mov_b32_e32 v7, v33
	v_lshl_add_u64 v[112:113], s[56:57], 0, v[8:9]
	v_lshl_add_u64 v[114:115], v[112:113], 0, v[6:7]
	v_mov_b32_e32 v1, v33
	v_mov_b32_e32 v3, v33
	s_mov_b64 s[62:63], 0
	s_waitcnt vmcnt(7)
	ds_write2_b32 v37, v24, v25 offset1:1
	ds_write2_b32 v37, v26, v27 offset0:2 offset1:3
	s_waitcnt vmcnt(6)
	ds_write2_b32 v79, v28, v29 offset1:1
	ds_write2_b32 v80, v30, v31 offset1:1
	s_waitcnt vmcnt(5)
	ds_write2_b32 v81, v56, v57 offset1:1
	ds_write2_b32 v82, v58, v59 offset1:1
	s_waitcnt vmcnt(4)
	ds_write2_b32 v83, v60, v61 offset1:1
	ds_write2_b32 v84, v62, v63 offset1:1
	s_waitcnt vmcnt(3)
	ds_write2_b32 v85, v96, v97 offset1:1
	ds_write2_b32 v86, v98, v99 offset1:1
	s_waitcnt vmcnt(2)
	ds_write2_b32 v87, v100, v101 offset1:1
	ds_write2_b32 v88, v102, v103 offset1:1
	s_waitcnt vmcnt(1)
	ds_write2_b32 v89, v104, v105 offset1:1
	ds_write2_b32 v90, v106, v107 offset1:1
	s_waitcnt vmcnt(0)
	ds_write2_b32 v91, v108, v109 offset1:1
	ds_write2_b32 v92, v110, v111 offset1:1
	s_waitcnt lgkmcnt(0)
	ds_read2_b32 v[24:25], v74 offset0:33 offset1:41
	ds_read2_b32 v[26:27], v74 offset0:66 offset1:74
	ds_read2_b32 v[28:29], v74 offset0:99 offset1:107
	ds_read2_b32 v[30:31], v74 offset1:8
	ds_read2_b32 v[56:57], v74 offset0:132 offset1:140
	ds_read2_b32 v[58:59], v74 offset0:165 offset1:173
	ds_read2_b32 v[60:61], v74 offset0:198 offset1:206
	ds_read2_b32 v[62:63], v74 offset0:231 offset1:239
	s_waitcnt lgkmcnt(4)
	v_mul_f32_e32 v5, 0x43000000, v30
	v_mul_f32_e32 v7, 0x43000000, v24
	v_mul_f32_e32 v23, 0x43000000, v31
	v_mul_f32_e32 v24, 0x43000000, v25
	v_mul_f32_e32 v9, 0x43000000, v26
	v_mul_f32_e32 v11, 0x43000000, v28
	v_mul_f32_e32 v25, 0x43000000, v27
	v_mul_f32_e32 v26, 0x43000000, v29
	v_med3_f32 v5, v5, s55, v93
	v_med3_f32 v7, v7, s55, v93
	v_med3_f32 v23, v23, s55, v93
	v_med3_f32 v24, v24, s55, v93
	s_waitcnt lgkmcnt(3)
	v_mul_f32_e32 v13, 0x43000000, v56
	s_waitcnt lgkmcnt(2)
	v_mul_f32_e32 v15, 0x43000000, v58
	v_mul_f32_e32 v27, 0x43000000, v57
	v_mul_f32_e32 v28, 0x43000000, v59
	v_med3_f32 v9, v9, s55, v93
	v_med3_f32 v11, v11, s55, v93
	v_med3_f32 v25, v25, s55, v93
	v_med3_f32 v26, v26, s55, v93
	v_cvt_scalef32_pk_fp4_f32 v1, v5, v7, 1.0
	v_cvt_scalef32_pk_fp4_f32 v3, v23, v24, 1.0
	s_waitcnt lgkmcnt(1)
	v_mul_f32_e32 v17, 0x43000000, v60
	s_waitcnt lgkmcnt(0)
	v_mul_f32_e32 v21, 0x43000000, v62
	v_mul_f32_e32 v29, 0x43000000, v61
	v_mul_f32_e32 v30, 0x43000000, v63
	v_med3_f32 v13, v13, s55, v93
	v_med3_f32 v15, v15, s55, v93
	v_med3_f32 v27, v27, s55, v93
	v_med3_f32 v28, v28, s55, v93
	v_cvt_scalef32_pk_fp4_f32 v1, v9, v11, 1.0 op_sel:[0,0,1,0]
	v_cvt_scalef32_pk_fp4_f32 v3, v25, v26, 1.0 op_sel:[0,0,1,0]
	v_med3_f32 v17, v17, s55, v93
	v_med3_f32 v21, v21, s55, v93
	v_med3_f32 v29, v29, s55, v93
	v_med3_f32 v30, v30, s55, v93
	v_cvt_scalef32_pk_fp4_f32 v1, v13, v15, 1.0 op_sel:[0,0,0,1]
	v_cvt_scalef32_pk_fp4_f32 v3, v27, v28, 1.0 op_sel:[0,0,0,1]
	v_mov_b32_e32 v5, v33
	v_cvt_scalef32_pk_fp4_f32 v1, v17, v21, 1.0 op_sel:[0,0,1,1]
	v_cvt_scalef32_pk_fp4_f32 v3, v29, v30, 1.0 op_sel:[0,0,1,1]
	v_lshl_add_u64 v[24:25], v[112:113], 0, v[4:5]
	global_store_dword v[114:115], v1, off
	global_store_dword v[24:25], v3, off
	ds_read2_b32 v[24:25], v74 offset0:49 offset1:57
	ds_read2_b32 v[26:27], v74 offset0:82 offset1:90
	ds_read2_b32 v[28:29], v74 offset0:115 offset1:123
	ds_read2_b32 v[30:31], v74 offset0:16 offset1:24
	ds_read2_b32 v[56:57], v74 offset0:148 offset1:156
	ds_read2_b32 v[58:59], v74 offset0:181 offset1:189
	ds_read2_b32 v[60:61], v74 offset0:214 offset1:222
	ds_read2_b32 v[62:63], v74 offset0:247 offset1:255
	s_waitcnt lgkmcnt(4)
	v_mul_f32_e32 v1, 0x43000000, v30
	v_mul_f32_e32 v3, 0x43000000, v24
	v_med3_f32 v1, v1, s55, v93
	v_med3_f32 v3, v3, s55, v93
	v_cvt_scalef32_pk_fp4_f32 v5, v1, v3, 1.0
	v_mul_f32_e32 v1, 0x43000000, v26
	v_mul_f32_e32 v3, 0x43000000, v28
	v_med3_f32 v1, v1, s55, v93
	v_med3_f32 v3, v3, s55, v93
	v_cvt_scalef32_pk_fp4_f32 v5, v1, v3, 1.0 op_sel:[0,0,1,0]
	s_waitcnt lgkmcnt(3)
	v_mul_f32_e32 v1, 0x43000000, v56
	s_waitcnt lgkmcnt(2)
	v_mul_f32_e32 v3, 0x43000000, v58
	v_med3_f32 v1, v1, s55, v93
	v_med3_f32 v3, v3, s55, v93
	v_cvt_scalef32_pk_fp4_f32 v5, v1, v3, 1.0 op_sel:[0,0,0,1]
	s_waitcnt lgkmcnt(1)
	v_mul_f32_e32 v1, 0x43000000, v60
	s_waitcnt lgkmcnt(0)
	v_mul_f32_e32 v3, 0x43000000, v62
	v_med3_f32 v1, v1, s55, v93
	v_med3_f32 v3, v3, s55, v93
	v_cvt_scalef32_pk_fp4_f32 v5, v1, v3, 1.0 op_sel:[0,0,1,1]
	v_mov_b32_e32 v3, v33
	v_lshl_add_u64 v[96:97], v[112:113], 0, v[2:3]
	v_mul_f32_e32 v1, 0x43000000, v31
	v_mul_f32_e32 v3, 0x43000000, v25
	global_store_dword v[96:97], v5, off
	v_med3_f32 v1, v1, s55, v93
	v_med3_f32 v3, v3, s55, v93
	v_mov_b32_e32 v5, v33
	v_cvt_scalef32_pk_fp4_f32 v5, v1, v3, 1.0
	v_mul_f32_e32 v1, 0x43000000, v27
	v_mul_f32_e32 v3, 0x43000000, v29
	v_med3_f32 v1, v1, s55, v93
	v_med3_f32 v3, v3, s55, v93
	v_cvt_scalef32_pk_fp4_f32 v5, v1, v3, 1.0 op_sel:[0,0,1,0]
	v_mul_f32_e32 v1, 0x43000000, v57
	v_mul_f32_e32 v3, 0x43000000, v59
	v_med3_f32 v1, v1, s55, v93
	v_med3_f32 v3, v3, s55, v93
	v_cvt_scalef32_pk_fp4_f32 v5, v1, v3, 1.0 op_sel:[0,0,0,1]
	v_mul_f32_e32 v1, 0x43000000, v61
	v_mul_f32_e32 v3, 0x43000000, v63
	v_med3_f32 v1, v1, s55, v93
	v_med3_f32 v3, v3, s55, v93
	v_cvt_scalef32_pk_fp4_f32 v5, v1, v3, 1.0 op_sel:[0,0,1,1]
	v_mov_b32_e32 v1, v33
	v_lshl_add_u64 v[24:25], v[112:113], 0, v[0:1]
	global_store_dword v[24:25], v5, off
	s_waitcnt lgkmcnt(0)

; __device__ __forceinline__ void p0_prologue(const Frame& F) {
;     ...
;         if (r < I_IN) { const int kb = r / NBO, nb = r % NBO;
;             if (nb < 192) { const int n0 = 32 * nb;
;                 const int r0 = n0 < 2048 ? (n0 >> 7) * 256 + (n0 & 127) : (n0 < 4096 ? 4096 + (n0 - 2048) : ((n0 - 4096) >> 7) * 256 + 128 + ((n0 - 4096) & 127));
;                 p0_transpose_item_cols(F.w_in, DM, NIN, n0, F.WinT16, r0, scr, kb, plane); }
.LBB0_40:
	s_andn2_b64 vcc, exec, s[58:59]
	s_cbranch_vccnz .LBB0_42
	s_and_b32 s0, s100, 0xf00
	s_and_b32 s58, s63, 0x60
	s_or_b32 s62, s58, s0
